# V
# speedup vs baseline: 1.0297x; 1.0031x over previous
.LBB0_323:
	v_lshl_add_u64 v[96:97], s[30:31], 0, v[144:145]
	v_add_co_u32_e32 v98, vcc, s90, v96
	v_lshl_add_u64 v[104:105], s[30:31], 0, v[146:147]
	s_nop 0
	v_addc_co_u32_e32 v99, vcc, 0, v97, vcc
	v_add_co_u32_e32 v100, vcc, s91, v96
	s_lshl_b64 s[8:9], 1, s58
	s_nop 0
	v_addc_co_u32_e32 v101, vcc, 0, v97, vcc
	v_add_co_u32_e32 v106, vcc, 0x3a800000, v104
	global_load_dwordx4 v[96:99], v[98:99], off offset:2048
	s_nop 0
	global_load_dwordx4 v[100:103], v[100:101], off offset:2048
	v_addc_co_u32_e32 v107, vcc, 0, v105, vcc
	v_add_co_u32_e32 v108, vcc, 0x3a880000, v104
	s_and_b32 s34, s58, 1
	s_nop 0
	v_addc_co_u32_e32 v109, vcc, 0, v105, vcc
	global_load_dwordx4 v[104:107], v[106:107], off offset:128
	s_nop 0
	global_load_dwordx4 v[108:111], v[108:109], off offset:128
	s_and_b64 s[10:11], s[8:9], s[16:17]
	s_cmp_eq_u64 s[10:11], 0
	s_cbranch_scc1 .LBB0_322
	s_mul_i32 s10, s34, 0x8c00
	v_add_u32_e32 v167, s10, v178
	v_add_u32_e32 v166, v167, v176
	ds_read_b128 v[112:115], v166
	ds_read_b128 v[116:119], v166 offset:64
	ds_read_b128 v[124:127], v166 offset:4352
	ds_read_b128 v[132:135], v166 offset:4416
	v_and_b32_e32 v169, s9, v163
	v_and_b32_e32 v168, s8, v162
	s_waitcnt lgkmcnt(3)
	v_mfma_f32_16x16x32_bf16 v[120:123], v[112:115], v[8:11], 0
	v_cmp_eq_u64_e64 s[10:11], 0, v[168:169]
	s_waitcnt lgkmcnt(1)
	v_mfma_f32_16x16x32_bf16 v[128:131], v[124:127], v[8:11], 0
	v_mfma_f32_16x16x32_bf16 v[136:139], v[124:127], v[24:27], 0
	ds_read_b128 v[124:127], v166 offset:8704
	ds_read_b128 v[148:151], v166 offset:8768
	ds_read_b128 v[156:159], v166 offset:13056
	ds_read_b128 v[196:199], v166 offset:13120
	ds_read_b128 v[204:207], v166 offset:128
	ds_read_b128 v[218:221], v166 offset:192
	v_mfma_f32_16x16x32_bf16 v[120:123], v[116:119], v[0:3], v[120:123]
	ds_read_b128 v[222:225], v166 offset:4480
	ds_read_b128 v[226:229], v166 offset:4544
	ds_read_b128 v[230:233], v166 offset:8832
	ds_read_b128 v[234:237], v166 offset:8896
	ds_read_b128 v[242:245], v166 offset:13184
	ds_read_b128 v[246:249], v166 offset:13248
	s_waitcnt lgkmcnt(11)
	v_mfma_f32_16x16x32_bf16 v[140:143], v[124:127], v[8:11], 0
	v_mfma_f32_16x16x32_bf16 v[152:155], v[124:127], v[24:27], 0
	s_waitcnt lgkmcnt(9)
	v_mfma_f32_16x16x32_bf16 v[124:127], v[156:159], v[8:11], 0
	v_mfma_f32_16x16x32_bf16 v[128:131], v[132:135], v[0:3], v[128:131]
	s_waitcnt lgkmcnt(7)
	v_mfma_f32_16x16x32_bf16 v[120:123], v[204:207], v[4:7], v[120:123]
	v_mfma_f32_16x16x32_bf16 v[140:143], v[148:151], v[0:3], v[140:143]
	v_mfma_f32_16x16x32_bf16 v[200:203], v[196:199], v[0:3], v[124:127]
	s_waitcnt lgkmcnt(5)
	v_mfma_f32_16x16x32_bf16 v[124:127], v[222:225], v[4:7], v[128:131]
	v_mfma_f32_16x16x32_bf16 v[128:131], v[218:221], v[12:15], v[120:123]
	s_waitcnt lgkmcnt(3)
	v_mfma_f32_16x16x32_bf16 v[238:241], v[230:233], v[4:7], v[140:143]
	v_mfma_f32_16x16x32_bf16 v[140:143], v[226:229], v[12:15], v[124:127]
	s_nop 4
	v_max_f32_e32 v120, v130, v131
	v_max3_f32 v166, v128, v129, v120
	s_waitcnt lgkmcnt(2)
	v_mfma_f32_16x16x32_bf16 v[124:127], v[234:237], v[12:15], v[238:241]
	v_max_f32_e32 v120, v142, v143
	v_max3_f32 v183, v140, v141, v120
	s_waitcnt lgkmcnt(1)
	v_mfma_f32_16x16x32_bf16 v[120:123], v[242:245], v[4:7], v[200:203]
	s_nop 1
	s_waitcnt lgkmcnt(0)
	v_mfma_f32_16x16x32_bf16 v[120:123], v[246:249], v[12:15], v[120:123]
	v_max_f32_e32 v191, v124, v125
	v_mfma_f32_16x16x32_bf16 v[112:115], v[112:115], v[24:27], 0
	v_max_f32_e32 v200, v126, v127
	s_nop 1
	s_nop 2
	v_max_f32_e32 v202, v122, v122
	v_max_f32_e32 v201, v202, v123
	v_max3_f32 v201, v120, v121, v201
	v_mfma_f32_16x16x32_bf16 v[112:115], v[116:119], v[16:19], v[112:115]
	v_max3_f32 v116, v191, v200, v201
	v_max3_f32 v116, v166, v183, v116
	v_mul_f32_e32 v166, 0x3e0293ee, v116
	v_mfma_f32_16x16x32_bf16 v[116:119], v[132:135], v[16:19], v[136:139]
	v_cndmask_b32_e64 v132, v166, v214, s[10:11]
	v_mov_b32_e32 v133, v132
	s_nop 1
	v_permlane16_swap_b32_e32 v132, v133
	v_mfma_f32_16x16x32_bf16 v[112:115], v[204:207], v[20:23], v[112:115]
	v_max_f32_e32 v132, v132, v133
	v_mfma_f32_16x16x32_bf16 v[156:159], v[156:159], v[24:27], 0
	v_mov_b32_e32 v133, v132
	s_nop 1
	v_permlane32_swap_b32_e32 v132, v133
	v_mfma_f32_16x16x32_bf16 v[116:119], v[222:225], v[20:23], v[116:119]
	v_mfma_f32_16x16x32_bf16 v[136:139], v[218:221], v[28:31], v[112:115]
	v_mfma_f32_16x16x32_bf16 v[148:151], v[148:151], v[16:19], v[152:155]
	v_mfma_f32_16x16x32_bf16 v[152:155], v[196:199], v[16:19], v[156:159]
	s_nop 5
	v_max_f32_e32 v112, v138, v139
	v_max_f32_e32 v158, v132, v133
	v_mfma_f32_16x16x32_bf16 v[132:135], v[226:229], v[28:31], v[116:119]
	v_max3_f32 v159, v136, v137, v112
	v_and_b32_e32 v157, s9, v161
	v_and_b32_e32 v156, s8, v160
	v_mfma_f32_16x16x32_bf16 v[112:115], v[230:233], v[20:23], v[148:151]
	v_cmp_eq_u64_e64 s[8:9], 0, v[156:157]
	s_nop 2
	v_max_f32_e32 v116, v134, v135
	v_max3_f32 v148, v132, v133, v116
	v_mfma_f32_16x16x32_bf16 v[116:119], v[234:237], v[28:31], v[112:115]
	s_nop 7
	v_max_f32_e32 v149, v116, v117
	v_mfma_f32_16x16x32_bf16 v[112:115], v[242:245], v[20:23], v[152:155]
	v_max_f32_e32 v150, v118, v119
	v_mfma_f32_16x16x32_bf16 v[112:115], v[246:249], v[28:31], v[112:115]
	s_nop 7
	v_max_f32_e32 v152, v114, v114
	v_max_f32_e32 v151, v152, v115
	v_max3_f32 v151, v112, v113, v151
	v_max3_f32 v149, v149, v150, v151
	v_max3_f32 v148, v159, v148, v149
	v_mul_f32_e32 v148, 0x3e0293ee, v148
	v_cndmask_b32_e64 v148, v148, v214, s[8:9]
	v_mov_b32_e32 v149, v148
	s_nop 1
	v_permlane16_swap_b32_e32 v148, v149
	v_max_f32_e32 v148, v148, v149
	v_mov_b32_e32 v149, v148
	s_nop 1
	v_permlane32_swap_b32_e32 v148, v149
	v_max_f32_e32 v150, v148, v149
	v_pk_add_f32 v[148:149], v[164:165], s[46:47] op_sel_hi:[1,0]
	s_nop 0
	v_cmp_gt_f32_e32 vcc, v150, v149
	s_nop 1
	v_cndmask_b32_e32 v149, v165, v150, vcc
	v_cmp_gt_f32_e32 vcc, v158, v148
	s_nop 1
	v_cndmask_b32_e32 v148, v164, v158, vcc
	v_pk_add_f32 v[150:151], v[164:165], v[148:149] neg_lo:[0,1] neg_hi:[0,1]
	s_nop 0
	v_exp_f32_e32 v150, v150
	v_exp_f32_e32 v151, v151
	v_cmp_neq_f32_e32 vcc, 1.0, v150
	v_cmp_neq_f32_e64 s[12:13], 1.0, v151
	s_or_b64 vcc, vcc, s[12:13]
	s_cbranch_vccz .LBB0_321
; template <int MODE> ...
;     ...
;       if (__ballot(alpha[0] != 1.0f || alpha[1] != 1.0f) != 0ull) {
; #pragma unroll
;         for (int qs = 0; qs < 2; ++qs)
; #pragma unroll
;           for (int dt = 0; dt < 8; ++dt) {
;             o[qs][dt][0] *= alpha[qs]; o[qs][dt][1] *= alpha[qs]; o[qs][dt][2] *= alpha[qs]; o[qs][dt][3] *= alpha[qs];
;           }
;       }
	v_mov_b32_e32 v152, v151
	v_pk_mul_f32 v[92:93], v[92:93], v[150:151] op_sel_hi:[1,0]
	v_pk_mul_f32 v[94:95], v[94:95], v[150:151] op_sel_hi:[1,0]
	v_pk_mul_f32 v[84:85], v[84:85], v[150:151] op_sel_hi:[1,0]
	v_pk_mul_f32 v[86:87], v[86:87], v[150:151] op_sel_hi:[1,0]
	v_pk_mul_f32 v[76:77], v[76:77], v[150:151] op_sel_hi:[1,0]
	v_pk_mul_f32 v[78:79], v[78:79], v[150:151] op_sel_hi:[1,0]
	v_pk_mul_f32 v[68:69], v[68:69], v[150:151] op_sel_hi:[1,0]
	v_pk_mul_f32 v[70:71], v[70:71], v[150:151] op_sel_hi:[1,0]
	v_pk_mul_f32 v[56:57], v[56:57], v[150:151] op_sel_hi:[1,0]
	v_pk_mul_f32 v[58:59], v[58:59], v[150:151] op_sel_hi:[1,0]
	v_pk_mul_f32 v[44:45], v[44:45], v[150:151] op_sel_hi:[1,0]
	v_pk_mul_f32 v[46:47], v[46:47], v[150:151] op_sel_hi:[1,0]
	v_pk_mul_f32 v[36:37], v[36:37], v[150:151] op_sel_hi:[1,0]
	v_pk_mul_f32 v[38:39], v[38:39], v[150:151] op_sel_hi:[1,0]
	v_pk_mul_f32 v[60:61], v[60:61], v[150:151] op_sel_hi:[1,0]
	v_pk_mul_f32 v[62:63], v[62:63], v[150:151] op_sel_hi:[1,0]
	v_pk_mul_f32 v[90:91], v[90:91], v[152:153] op_sel_hi:[1,0]
	v_pk_mul_f32 v[88:89], v[88:89], v[152:153] op_sel_hi:[1,0]
	v_pk_mul_f32 v[82:83], v[82:83], v[152:153] op_sel_hi:[1,0]
	v_pk_mul_f32 v[80:81], v[80:81], v[152:153] op_sel_hi:[1,0]
	v_pk_mul_f32 v[74:75], v[74:75], v[152:153] op_sel_hi:[1,0]
	v_pk_mul_f32 v[72:73], v[72:73], v[152:153] op_sel_hi:[1,0]
	v_pk_mul_f32 v[66:67], v[66:67], v[152:153] op_sel_hi:[1,0]
	v_pk_mul_f32 v[64:65], v[64:65], v[152:153] op_sel_hi:[1,0]
	v_pk_mul_f32 v[54:55], v[54:55], v[152:153] op_sel_hi:[1,0]
	v_pk_mul_f32 v[52:53], v[52:53], v[152:153] op_sel_hi:[1,0]
	v_pk_mul_f32 v[42:43], v[42:43], v[152:153] op_sel_hi:[1,0]
	v_pk_mul_f32 v[40:41], v[40:41], v[152:153] op_sel_hi:[1,0]
	v_pk_mul_f32 v[34:35], v[34:35], v[152:153] op_sel_hi:[1,0]
	v_pk_mul_f32 v[32:33], v[32:33], v[152:153] op_sel_hi:[1,0]
	v_pk_mul_f32 v[50:51], v[50:51], v[152:153] op_sel_hi:[1,0]
	v_pk_mul_f32 v[48:49], v[48:49], v[152:153] op_sel_hi:[1,0]
	s_branch .LBB0_321

; template <int MODE> ...
;     ...
;       float alpha[2];
; #pragma unroll
;       for (int qs = 0; qs < 2; ++qs) {
;         const bool sel = (MODE == 1) ? true : (bool)((mymask[qs] >> j) & 1ull);
;         float mx4[4];
; #pragma unroll
;         for (int mt = 0; mt < 4; ++mt)
;           mx4[mt] = fmaxf(fmaxf(s[qs][mt][0], s[qs][mt][1]), fmaxf(s[qs][mt][2], s[qs][mt][3]));
;         float mx = fmaxf(fmaxf(mx4[0], mx4[1]), fmaxf(mx4[2], mx4[3]));
;         mx = sel ? mx * SCL : -1e30f;
;         mx = quad_max(mx);
;         const float m_new = (mx > m_run[qs] + RESCALE_THR) ? mx : m_run[qs];
;         alpha[qs] = __builtin_amdgcn_exp2f(m_run[qs] - m_new);
;         m_run[qs] = m_new;
;         const float negm = sel ? -m_new : -1e30f;
;         float ps4[4];
; #pragma unroll
;         for (int mt = 0; mt < 4; ++mt) {
; #pragma unroll
;           for (int jj = 0; jj < 4; ++jj) s[qs][mt][jj] = __builtin_amdgcn_exp2f(fmaf(s[qs][mt][jj], SCL, negm));
;           ps4[mt] = (s[qs][mt][0] + s[qs][mt][1]) + (s[qs][mt][2] + s[qs][mt][3]);
;         }
;         l_run[qs] = l_run[qs] * alpha[qs] + ((ps4[0] + ps4[1]) + (ps4[2] + ps4[3]));
; #pragma unroll
;         for (int kk = 0; kk < 2; ++kk) {
;           uint4 pk;
;           pk.x = pack2(s[qs][2 * kk][0], s[qs][2 * kk][1]);
;           pk.y = pack2(s[qs][2 * kk][2], s[qs][2 * kk][3]);
;           pk.z = pack2(s[qs][2 * kk + 1][0], s[qs][2 * kk + 1][1]);
;           pk.w = pack2(s[qs][2 * kk + 1][2], s[qs][2 * kk + 1][3]);
;           pb[qs][kk] = *reinterpret_cast<bf16x8*>(&pk);
;         }
;       }
;       if (__ballot(alpha[0] != 1.0f || alpha[1] != 1.0f) != 0ull) {
; #pragma unroll
;         for (int qs = 0; qs < 2; ++qs)
; #pragma unroll
;           for (int dt = 0; dt < 8; ++dt) {
;             o[qs][dt][0] *= alpha[qs]; o[qs][dt][1] *= alpha[qs]; o[qs][dt][2] *= alpha[qs]; o[qs][dt][3] *= alpha[qs];
;           }
;       }
.LBB0_341:
	v_max_f32_e32 v154, v142, v143
	v_max_f32_e32 v155, v138, v139
	s_nop 0
	v_max_f32_e32 v156, v116, v117
	v_max_f32_e32 v158, v118, v119
	s_nop 0
	v_max_f32_e32 v159, v126, v127
	v_max3_f32 v159, v124, v125, v159
	v_max3_f32 v154, v140, v141, v154
	v_max3_f32 v155, v136, v137, v155
	v_max3_f32 v156, v156, v158, v159
	v_max3_f32 v154, v154, v155, v156
	v_mul_f32_e32 v154, 0x3e0293ee, v154
	v_mov_b32_e32 v155, v154
	s_nop 1
	v_permlane16_swap_b32_e32 v154, v155
	v_max_f32_e32 v154, v154, v155
	v_mov_b32_e32 v155, v154
	s_nop 1
	v_permlane32_swap_b32_e32 v154, v155
	v_max_f32_e32 v156, v154, v155
	v_max_f32_e32 v154, v134, v135
	v_max_f32_e32 v155, v130, v131
	v_max_f32_e32 v158, v112, v113
	v_max_f32_e32 v159, v114, v115
	v_max_f32_e32 v161, v122, v122
	v_max_f32_e32 v160, v161, v123
	v_max3_f32 v160, v120, v121, v160
	v_max3_f32 v154, v132, v133, v154
	v_max3_f32 v155, v128, v129, v155
	v_max3_f32 v158, v158, v159, v160
	v_max3_f32 v154, v154, v155, v158
	v_mul_f32_e32 v154, 0x3e0293ee, v154
	v_mov_b32_e32 v155, v154
	s_nop 1
	v_permlane16_swap_b32_e32 v154, v155
	v_max_f32_e32 v154, v154, v155
	v_mov_b32_e32 v155, v154
	s_nop 1
	v_permlane32_swap_b32_e32 v154, v155
	v_mov_b32_e32 v152, v150
	v_mov_b32_e32 v153, v151
	v_max_f32_e32 v158, v154, v155
	v_pk_add_f32 v[154:155], v[152:153], s[46:47] op_sel_hi:[1,0]
	s_nop 0
	v_cmp_gt_f32_e32 vcc, v158, v155
	s_nop 1
	v_cndmask_b32_e32 v151, v151, v158, vcc
	v_cmp_gt_f32_e32 vcc, v156, v154
	s_nop 1
	v_cndmask_b32_e32 v150, v150, v156, vcc
	v_pk_add_f32 v[152:153], v[152:153], v[150:151] neg_lo:[0,1] neg_hi:[0,1]
	s_nop 0
	v_exp_f32_e32 v152, v152
	v_exp_f32_e32 v153, v153
	v_cmp_neq_f32_e32 vcc, 1.0, v152
	v_cmp_neq_f32_e64 s[8:9], 1.0, v153
	s_or_b64 vcc, vcc, s[8:9]
	s_cbranch_vccz .LBB0_343
	v_mov_b32_e32 v154, v153
	v_pk_mul_f32 v[92:93], v[92:93], v[152:153] op_sel_hi:[1,0]
	v_pk_mul_f32 v[94:95], v[94:95], v[152:153] op_sel_hi:[1,0]
	v_pk_mul_f32 v[88:89], v[88:89], v[152:153] op_sel_hi:[1,0]
	v_pk_mul_f32 v[90:91], v[90:91], v[152:153] op_sel_hi:[1,0]
	v_pk_mul_f32 v[84:85], v[84:85], v[152:153] op_sel_hi:[1,0]
	v_pk_mul_f32 v[86:87], v[86:87], v[152:153] op_sel_hi:[1,0]
	v_pk_mul_f32 v[80:81], v[80:81], v[152:153] op_sel_hi:[1,0]
	v_pk_mul_f32 v[82:83], v[82:83], v[152:153] op_sel_hi:[1,0]
	v_pk_mul_f32 v[76:77], v[76:77], v[152:153] op_sel_hi:[1,0]
	v_pk_mul_f32 v[78:79], v[78:79], v[152:153] op_sel_hi:[1,0]
	v_pk_mul_f32 v[72:73], v[72:73], v[152:153] op_sel_hi:[1,0]
	v_pk_mul_f32 v[74:75], v[74:75], v[152:153] op_sel_hi:[1,0]
	v_pk_mul_f32 v[68:69], v[68:69], v[152:153] op_sel_hi:[1,0]
	v_pk_mul_f32 v[70:71], v[70:71], v[152:153] op_sel_hi:[1,0]
	v_pk_mul_f32 v[64:65], v[64:65], v[152:153] op_sel_hi:[1,0]
	v_pk_mul_f32 v[66:67], v[66:67], v[152:153] op_sel_hi:[1,0]
	v_pk_mul_f32 v[62:63], v[62:63], v[154:155] op_sel_hi:[1,0]
	v_pk_mul_f32 v[60:61], v[60:61], v[154:155] op_sel_hi:[1,0]
	v_pk_mul_f32 v[58:59], v[58:59], v[154:155] op_sel_hi:[1,0]
	v_pk_mul_f32 v[56:57], v[56:57], v[154:155] op_sel_hi:[1,0]
	v_pk_mul_f32 v[54:55], v[54:55], v[154:155] op_sel_hi:[1,0]
	v_pk_mul_f32 v[52:53], v[52:53], v[154:155] op_sel_hi:[1,0]
	v_pk_mul_f32 v[50:51], v[50:51], v[154:155] op_sel_hi:[1,0]
	v_pk_mul_f32 v[48:49], v[48:49], v[154:155] op_sel_hi:[1,0]
	v_pk_mul_f32 v[46:47], v[46:47], v[154:155] op_sel_hi:[1,0]
	v_pk_mul_f32 v[44:45], v[44:45], v[154:155] op_sel_hi:[1,0]
	v_pk_mul_f32 v[42:43], v[42:43], v[154:155] op_sel_hi:[1,0]
	v_pk_mul_f32 v[40:41], v[40:41], v[154:155] op_sel_hi:[1,0]
	v_pk_mul_f32 v[38:39], v[38:39], v[154:155] op_sel_hi:[1,0]
	v_pk_mul_f32 v[36:37], v[36:37], v[154:155] op_sel_hi:[1,0]
	v_pk_mul_f32 v[34:35], v[34:35], v[154:155] op_sel_hi:[1,0]
	v_pk_mul_f32 v[32:33], v[32:33], v[154:155] op_sel_hi:[1,0]

.LBB0_659:
	v_lshl_add_u64 v[96:97], s[24:25], 0, v[144:145]
	v_add_co_u32_e32 v98, vcc, s90, v96
	v_lshl_add_u64 v[104:105], s[24:25], 0, v[146:147]
	s_nop 0
	v_addc_co_u32_e32 v99, vcc, 0, v97, vcc
	v_add_co_u32_e32 v100, vcc, s91, v96
	s_lshl_b64 s[10:11], 1, s60
	s_nop 0
	v_addc_co_u32_e32 v101, vcc, 0, v97, vcc
	v_add_co_u32_e32 v106, vcc, 0x3a800000, v104
	global_load_dwordx4 v[96:99], v[98:99], off offset:2048
	s_nop 0
	global_load_dwordx4 v[100:103], v[100:101], off offset:2048
	v_addc_co_u32_e32 v107, vcc, 0, v105, vcc
	v_add_co_u32_e32 v108, vcc, 0x3a880000, v104
	s_and_b32 s8, s60, 1
	s_nop 0
	v_addc_co_u32_e32 v109, vcc, 0, v105, vcc
	global_load_dwordx4 v[104:107], v[106:107], off offset:128
	s_nop 0
	global_load_dwordx4 v[108:111], v[108:109], off offset:128
	s_and_b64 s[6:7], s[10:11], s[16:17]
	s_cmp_eq_u64 s[6:7], 0
	s_cbranch_scc1 .LBB0_658
	s_mul_i32 s6, s8, 0x8c00
	v_add_u32_e32 v157, s6, v174
	v_add_u32_e32 v156, v157, v171
	ds_read_b128 v[112:115], v156
	ds_read_b128 v[148:151], v156 offset:64
	ds_read_b128 v[120:123], v156 offset:4352
	ds_read_b128 v[128:131], v156 offset:8704
	ds_read_b128 v[136:139], v156 offset:13056
	s_waitcnt lgkmcnt(4)
	v_mfma_f32_16x16x32_bf16 v[116:119], v[112:115], v[8:11], 0
	v_mfma_f32_16x16x32_bf16 v[112:115], v[112:115], v[24:27], 0
	s_waitcnt lgkmcnt(3)
	v_mfma_f32_16x16x32_bf16 v[116:119], v[148:151], v[0:3], v[116:119]
	v_mfma_f32_16x16x32_bf16 v[112:115], v[148:151], v[16:19], v[112:115]
	ds_read_b128 v[148:151], v156 offset:4416
	s_waitcnt lgkmcnt(3)
	v_mfma_f32_16x16x32_bf16 v[124:127], v[120:123], v[8:11], 0
	v_mfma_f32_16x16x32_bf16 v[120:123], v[120:123], v[24:27], 0
	s_waitcnt lgkmcnt(0)
	v_mfma_f32_16x16x32_bf16 v[124:127], v[148:151], v[0:3], v[124:127]
	v_mfma_f32_16x16x32_bf16 v[120:123], v[148:151], v[16:19], v[120:123]
	ds_read_b128 v[148:151], v156 offset:8768
	v_mfma_f32_16x16x32_bf16 v[132:135], v[128:131], v[8:11], 0
	v_mfma_f32_16x16x32_bf16 v[128:131], v[128:131], v[24:27], 0
	s_waitcnt lgkmcnt(0)
	v_mfma_f32_16x16x32_bf16 v[132:135], v[148:151], v[0:3], v[132:135]
	v_mfma_f32_16x16x32_bf16 v[128:131], v[148:151], v[16:19], v[128:131]
	ds_read_b128 v[148:151], v156 offset:13120
	v_mfma_f32_16x16x32_bf16 v[140:143], v[136:139], v[8:11], 0
	v_mfma_f32_16x16x32_bf16 v[136:139], v[136:139], v[24:27], 0
	s_waitcnt lgkmcnt(0)
	v_mfma_f32_16x16x32_bf16 v[140:143], v[148:151], v[0:3], v[140:143]
	v_mfma_f32_16x16x32_bf16 v[136:139], v[148:151], v[16:19], v[136:139]
	ds_read_b128 v[148:151], v156 offset:128
	s_waitcnt lgkmcnt(0)
	v_mfma_f32_16x16x32_bf16 v[116:119], v[148:151], v[4:7], v[116:119]
	v_mfma_f32_16x16x32_bf16 v[112:115], v[148:151], v[20:23], v[112:115]
	ds_read_b128 v[148:151], v156 offset:4480
	s_waitcnt lgkmcnt(0)
	v_mfma_f32_16x16x32_bf16 v[124:127], v[148:151], v[4:7], v[124:127]
	v_mfma_f32_16x16x32_bf16 v[120:123], v[148:151], v[20:23], v[120:123]
	ds_read_b128 v[148:151], v156 offset:8832
	s_waitcnt lgkmcnt(0)
	v_mfma_f32_16x16x32_bf16 v[152:155], v[148:151], v[4:7], v[132:135]
	v_mfma_f32_16x16x32_bf16 v[148:151], v[148:151], v[20:23], v[128:131]
	s_nop 2
	ds_read_b128 v[128:131], v156 offset:13184
	s_waitcnt lgkmcnt(0)
	v_mfma_f32_16x16x32_bf16 v[176:179], v[128:131], v[4:7], v[140:143]
	v_mfma_f32_16x16x32_bf16 v[196:199], v[128:131], v[20:23], v[136:139]
	ds_read_b128 v[128:131], v156 offset:192
	s_waitcnt lgkmcnt(0)
	v_mfma_f32_16x16x32_bf16 v[132:135], v[128:131], v[28:31], v[112:115]
	s_nop 2
	ds_read_b128 v[112:115], v156 offset:4544
	v_mfma_f32_16x16x32_bf16 v[136:139], v[128:131], v[12:15], v[116:119]
	s_nop 2
	ds_read_b128 v[116:119], v156 offset:13248
	s_waitcnt lgkmcnt(1)
	v_mfma_f32_16x16x32_bf16 v[140:143], v[112:115], v[12:15], v[124:127]
	v_mfma_f32_16x16x32_bf16 v[128:131], v[112:115], v[28:31], v[120:123]
	ds_read_b128 v[112:115], v156 offset:8896
	s_waitcnt lgkmcnt(0)
	v_mfma_f32_16x16x32_bf16 v[124:127], v[112:115], v[12:15], v[152:155]
	s_nop 3
	s_nop 2
	v_mfma_f32_16x16x32_bf16 v[112:115], v[112:115], v[28:31], v[148:151]
	v_mfma_f32_16x16x32_bf16 v[120:123], v[116:119], v[12:15], v[176:179]
	s_nop 0
	s_nop 0
	v_max_f32_e32 v150, v138, v139
	v_max_f32_e32 v151, v142, v143
	v_max_f32_e32 v152, v124, v125
	v_max_f32_e32 v153, v126, v127
	s_nop 1
	v_max_f32_e32 v154, v122, v123
	v_and_b32_e32 v149, s11, v163
	v_and_b32_e32 v148, s10, v162
	v_max3_f32 v154, v120, v121, v154
	v_max3_f32 v150, v136, v137, v150
	v_max3_f32 v151, v140, v141, v151
	v_cmp_eq_u64_e64 s[6:7], 0, v[148:149]
	v_max3_f32 v148, v152, v153, v154
	v_max3_f32 v148, v150, v151, v148
	v_mul_f32_e32 v148, 0x3e0293ee, v148
	v_cndmask_b32_e64 v148, v148, v214, s[6:7]
	v_mov_b32_e32 v149, v148
	v_mfma_f32_16x16x32_bf16 v[116:119], v[116:119], v[28:31], v[196:199]
	s_nop 0
	v_permlane16_swap_b32_e32 v148, v149
	v_max_f32_e32 v151, v134, v135
	v_max_f32_e32 v148, v148, v149
	v_max_f32_e32 v152, v130, v131
	v_mov_b32_e32 v149, v148
	v_max_f32_e32 v153, v112, v113
	s_nop 0
	v_permlane32_swap_b32_e32 v148, v149
	v_max_f32_e32 v154, v114, v115
	v_max_f32_e32 v156, v118, v118
	v_max_f32_e32 v155, v156, v119
	v_max_f32_e32 v150, v148, v149
	v_and_b32_e32 v149, s11, v161
	v_and_b32_e32 v148, s10, v160
	v_max3_f32 v155, v116, v117, v155
	v_max3_f32 v151, v132, v133, v151
	v_max3_f32 v152, v128, v129, v152
	v_cmp_eq_u64_e64 s[10:11], 0, v[148:149]
	v_max3_f32 v148, v153, v154, v155
	v_max3_f32 v148, v151, v152, v148
	v_mul_f32_e32 v148, 0x3e0293ee, v148
	v_cndmask_b32_e64 v148, v148, v214, s[10:11]
	v_mov_b32_e32 v149, v148
	s_nop 1
	v_permlane16_swap_b32_e32 v148, v149
	v_max_f32_e32 v148, v148, v149
	v_mov_b32_e32 v149, v148
	s_nop 1
	v_permlane32_swap_b32_e32 v148, v149
	v_max_f32_e32 v151, v148, v149
	v_pk_add_f32 v[148:149], v[164:165], s[48:49] op_sel_hi:[1,0]
	s_nop 0
	v_cmp_gt_f32_e32 vcc, v150, v148
	v_cmp_gt_f32_e64 s[12:13], v151, v149
	s_nop 0
	v_cndmask_b32_e32 v148, v164, v150, vcc
	v_cndmask_b32_e64 v149, v165, v151, s[12:13]
	v_pk_add_f32 v[150:151], v[164:165], v[148:149] neg_lo:[0,1] neg_hi:[0,1]
	s_nop 0
	v_exp_f32_e32 v150, v150
	v_exp_f32_e32 v151, v151
	v_cmp_neq_f32_e32 vcc, 1.0, v150
	v_cmp_neq_f32_e64 s[12:13], 1.0, v151
	s_or_b64 vcc, vcc, s[12:13]
	s_cbranch_vccz .LBB0_657
; template <int MODE> ...
;     ...
;       if (__ballot(alpha[0] != 1.0f || alpha[1] != 1.0f) != 0ull) {
; #pragma unroll
;         for (int qs = 0; qs < 2; ++qs)
; #pragma unroll
;           for (int dt = 0; dt < 8; ++dt) {
;             o[qs][dt][0] *= alpha[qs]; o[qs][dt][1] *= alpha[qs]; o[qs][dt][2] *= alpha[qs]; o[qs][dt][3] *= alpha[qs];
;           }
;       }
	v_mov_b32_e32 v152, v151
	v_pk_mul_f32 v[92:93], v[92:93], v[150:151] op_sel_hi:[1,0]
	v_pk_mul_f32 v[94:95], v[94:95], v[150:151] op_sel_hi:[1,0]
	v_pk_mul_f32 v[84:85], v[84:85], v[150:151] op_sel_hi:[1,0]
	v_pk_mul_f32 v[86:87], v[86:87], v[150:151] op_sel_hi:[1,0]
	v_pk_mul_f32 v[76:77], v[76:77], v[150:151] op_sel_hi:[1,0]
	v_pk_mul_f32 v[78:79], v[78:79], v[150:151] op_sel_hi:[1,0]
	v_pk_mul_f32 v[68:69], v[68:69], v[150:151] op_sel_hi:[1,0]
	v_pk_mul_f32 v[70:71], v[70:71], v[150:151] op_sel_hi:[1,0]
	v_pk_mul_f32 v[60:61], v[60:61], v[150:151] op_sel_hi:[1,0]
	v_pk_mul_f32 v[62:63], v[62:63], v[150:151] op_sel_hi:[1,0]
	v_pk_mul_f32 v[52:53], v[52:53], v[150:151] op_sel_hi:[1,0]
	v_pk_mul_f32 v[54:55], v[54:55], v[150:151] op_sel_hi:[1,0]
	v_pk_mul_f32 v[44:45], v[44:45], v[150:151] op_sel_hi:[1,0]
	v_pk_mul_f32 v[46:47], v[46:47], v[150:151] op_sel_hi:[1,0]
	v_pk_mul_f32 v[36:37], v[36:37], v[150:151] op_sel_hi:[1,0]
	v_pk_mul_f32 v[38:39], v[38:39], v[150:151] op_sel_hi:[1,0]
	v_pk_mul_f32 v[90:91], v[90:91], v[152:153] op_sel_hi:[1,0]
	v_pk_mul_f32 v[88:89], v[88:89], v[152:153] op_sel_hi:[1,0]
	v_pk_mul_f32 v[82:83], v[82:83], v[152:153] op_sel_hi:[1,0]
	v_pk_mul_f32 v[80:81], v[80:81], v[152:153] op_sel_hi:[1,0]
	v_pk_mul_f32 v[74:75], v[74:75], v[152:153] op_sel_hi:[1,0]
	v_pk_mul_f32 v[72:73], v[72:73], v[152:153] op_sel_hi:[1,0]
	v_pk_mul_f32 v[66:67], v[66:67], v[152:153] op_sel_hi:[1,0]
	v_pk_mul_f32 v[64:65], v[64:65], v[152:153] op_sel_hi:[1,0]
	v_pk_mul_f32 v[58:59], v[58:59], v[152:153] op_sel_hi:[1,0]
	v_pk_mul_f32 v[56:57], v[56:57], v[152:153] op_sel_hi:[1,0]
	v_pk_mul_f32 v[50:51], v[50:51], v[152:153] op_sel_hi:[1,0]
	v_pk_mul_f32 v[48:49], v[48:49], v[152:153] op_sel_hi:[1,0]
	v_pk_mul_f32 v[42:43], v[42:43], v[152:153] op_sel_hi:[1,0]
	v_pk_mul_f32 v[40:41], v[40:41], v[152:153] op_sel_hi:[1,0]
	v_pk_mul_f32 v[34:35], v[34:35], v[152:153] op_sel_hi:[1,0]
	v_pk_mul_f32 v[32:33], v[32:33], v[152:153] op_sel_hi:[1,0]
	s_branch .LBB0_657

; template <int MODE> ...
;     ...
;       float alpha[2];
; #pragma unroll
;       for (int qs = 0; qs < 2; ++qs) {
;         const bool sel = (MODE == 1) ? true : (bool)((mymask[qs] >> j) & 1ull);
;         float mx4[4];
; #pragma unroll
;         for (int mt = 0; mt < 4; ++mt)
;           mx4[mt] = fmaxf(fmaxf(s[qs][mt][0], s[qs][mt][1]), fmaxf(s[qs][mt][2], s[qs][mt][3]));
;         float mx = fmaxf(fmaxf(mx4[0], mx4[1]), fmaxf(mx4[2], mx4[3]));
;         mx = sel ? mx * SCL : -1e30f;
;         mx = quad_max(mx);
;         const float m_new = (mx > m_run[qs] + RESCALE_THR) ? mx : m_run[qs];
;         alpha[qs] = __builtin_amdgcn_exp2f(m_run[qs] - m_new);
;         m_run[qs] = m_new;
;         const float negm = sel ? -m_new : -1e30f;
;         float ps4[4];
; #pragma unroll
;         for (int mt = 0; mt < 4; ++mt) {
; #pragma unroll
;           for (int jj = 0; jj < 4; ++jj) s[qs][mt][jj] = __builtin_amdgcn_exp2f(fmaf(s[qs][mt][jj], SCL, negm));
;           ps4[mt] = (s[qs][mt][0] + s[qs][mt][1]) + (s[qs][mt][2] + s[qs][mt][3]);
;         }
;         l_run[qs] = l_run[qs] * alpha[qs] + ((ps4[0] + ps4[1]) + (ps4[2] + ps4[3]));
; #pragma unroll
;         for (int kk = 0; kk < 2; ++kk) {
;           uint4 pk;
;           pk.x = pack2(s[qs][2 * kk][0], s[qs][2 * kk][1]);
;           pk.y = pack2(s[qs][2 * kk][2], s[qs][2 * kk][3]);
;           pk.z = pack2(s[qs][2 * kk + 1][0], s[qs][2 * kk + 1][1]);
;           pk.w = pack2(s[qs][2 * kk + 1][2], s[qs][2 * kk + 1][3]);
;           pb[qs][kk] = *reinterpret_cast<bf16x8*>(&pk);
;         }
;       }
;       if (__ballot(alpha[0] != 1.0f || alpha[1] != 1.0f) != 0ull) {
; #pragma unroll
;         for (int qs = 0; qs < 2; ++qs)
; #pragma unroll
;           for (int dt = 0; dt < 8; ++dt) {
;             o[qs][dt][0] *= alpha[qs]; o[qs][dt][1] *= alpha[qs]; o[qs][dt][2] *= alpha[qs]; o[qs][dt][3] *= alpha[qs];
;           }
;       }
.LBB0_677:
	v_max_f32_e32 v154, v142, v143
	v_max_f32_e32 v155, v138, v139
	s_nop 0
	v_max_f32_e32 v156, v124, v125
	v_max_f32_e32 v158, v126, v127
	s_nop 0
	v_max_f32_e32 v159, v122, v123
	v_max3_f32 v159, v120, v121, v159
	v_max3_f32 v154, v140, v141, v154
	v_max3_f32 v155, v136, v137, v155
	v_max3_f32 v156, v156, v158, v159
	v_max3_f32 v154, v154, v155, v156
	v_mul_f32_e32 v154, 0x3e0293ee, v154
	v_mov_b32_e32 v155, v154
	s_nop 1
	v_permlane16_swap_b32_e32 v154, v155
	v_max_f32_e32 v154, v154, v155
	v_mov_b32_e32 v155, v154
	s_nop 1
	v_permlane32_swap_b32_e32 v154, v155
	v_max_f32_e32 v156, v154, v155
	v_max_f32_e32 v154, v134, v135
	v_max_f32_e32 v155, v130, v131
	v_max_f32_e32 v158, v112, v113
	v_max_f32_e32 v159, v114, v115
	v_max_f32_e32 v161, v118, v118
	v_max_f32_e32 v160, v161, v119
	v_max3_f32 v160, v116, v117, v160
	v_max3_f32 v154, v132, v133, v154
	v_max3_f32 v155, v128, v129, v155
	v_max3_f32 v158, v158, v159, v160
	v_max3_f32 v154, v154, v155, v158
	v_mul_f32_e32 v154, 0x3e0293ee, v154
	v_mov_b32_e32 v155, v154
	s_nop 1
	v_permlane16_swap_b32_e32 v154, v155
	v_max_f32_e32 v154, v154, v155
	v_mov_b32_e32 v155, v154
	s_nop 1
	v_permlane32_swap_b32_e32 v154, v155
	v_mov_b32_e32 v152, v150
	v_mov_b32_e32 v153, v151
	v_max_f32_e32 v158, v154, v155
	v_pk_add_f32 v[154:155], v[152:153], s[48:49] op_sel_hi:[1,0]
	s_nop 0
	v_cmp_gt_f32_e32 vcc, v158, v155
	s_nop 1
	v_cndmask_b32_e32 v151, v151, v158, vcc
	v_cmp_gt_f32_e32 vcc, v156, v154
	s_nop 1
	v_cndmask_b32_e32 v150, v150, v156, vcc
	v_pk_add_f32 v[152:153], v[152:153], v[150:151] neg_lo:[0,1] neg_hi:[0,1]
	s_nop 0
	v_exp_f32_e32 v152, v152
	v_exp_f32_e32 v153, v153
	v_cmp_neq_f32_e32 vcc, 1.0, v152
	v_cmp_neq_f32_e64 s[6:7], 1.0, v153
	s_or_b64 vcc, vcc, s[6:7]
	s_cbranch_vccz .LBB0_679
	v_mov_b32_e32 v154, v153
	v_pk_mul_f32 v[92:93], v[92:93], v[152:153] op_sel_hi:[1,0]
	v_pk_mul_f32 v[94:95], v[94:95], v[152:153] op_sel_hi:[1,0]
	v_pk_mul_f32 v[88:89], v[88:89], v[152:153] op_sel_hi:[1,0]
	v_pk_mul_f32 v[90:91], v[90:91], v[152:153] op_sel_hi:[1,0]
	v_pk_mul_f32 v[84:85], v[84:85], v[152:153] op_sel_hi:[1,0]
	v_pk_mul_f32 v[86:87], v[86:87], v[152:153] op_sel_hi:[1,0]
	v_pk_mul_f32 v[80:81], v[80:81], v[152:153] op_sel_hi:[1,0]
	v_pk_mul_f32 v[82:83], v[82:83], v[152:153] op_sel_hi:[1,0]
	v_pk_mul_f32 v[76:77], v[76:77], v[152:153] op_sel_hi:[1,0]
	v_pk_mul_f32 v[78:79], v[78:79], v[152:153] op_sel_hi:[1,0]
	v_pk_mul_f32 v[72:73], v[72:73], v[152:153] op_sel_hi:[1,0]
	v_pk_mul_f32 v[74:75], v[74:75], v[152:153] op_sel_hi:[1,0]
	v_pk_mul_f32 v[68:69], v[68:69], v[152:153] op_sel_hi:[1,0]
	v_pk_mul_f32 v[70:71], v[70:71], v[152:153] op_sel_hi:[1,0]
	v_pk_mul_f32 v[64:65], v[64:65], v[152:153] op_sel_hi:[1,0]
	v_pk_mul_f32 v[66:67], v[66:67], v[152:153] op_sel_hi:[1,0]
	v_pk_mul_f32 v[62:63], v[62:63], v[154:155] op_sel_hi:[1,0]
	v_pk_mul_f32 v[60:61], v[60:61], v[154:155] op_sel_hi:[1,0]
	v_pk_mul_f32 v[58:59], v[58:59], v[154:155] op_sel_hi:[1,0]
	v_pk_mul_f32 v[56:57], v[56:57], v[154:155] op_sel_hi:[1,0]
	v_pk_mul_f32 v[54:55], v[54:55], v[154:155] op_sel_hi:[1,0]
	v_pk_mul_f32 v[52:53], v[52:53], v[154:155] op_sel_hi:[1,0]
	v_pk_mul_f32 v[50:51], v[50:51], v[154:155] op_sel_hi:[1,0]
	v_pk_mul_f32 v[48:49], v[48:49], v[154:155] op_sel_hi:[1,0]
	v_pk_mul_f32 v[46:47], v[46:47], v[154:155] op_sel_hi:[1,0]
	v_pk_mul_f32 v[44:45], v[44:45], v[154:155] op_sel_hi:[1,0]
	v_pk_mul_f32 v[42:43], v[42:43], v[154:155] op_sel_hi:[1,0]
	v_pk_mul_f32 v[40:41], v[40:41], v[154:155] op_sel_hi:[1,0]
	v_pk_mul_f32 v[38:39], v[38:39], v[154:155] op_sel_hi:[1,0]
	v_pk_mul_f32 v[36:37], v[36:37], v[154:155] op_sel_hi:[1,0]
	v_pk_mul_f32 v[34:35], v[34:35], v[154:155] op_sel_hi:[1,0]
	v_pk_mul_f32 v[32:33], v[32:33], v[154:155] op_sel_hi:[1,0]
